# P5: residual loads of epilogue row groups 2-5 prefetched from inside the K-loop (4 iterations before its end)
# speedup vs baseline: 1.0014x; 1.0004x over previous
; __device__ __forceinline__ f32x4 bf4_to_f32(u32x2 w) { f32x4 r; r[0] = __uint_as_float(w.x << 16); r[1] = __uint_as_float(w.x & 0xffff0000u); r[2] = __uint_as_float(w.y << 16); r[3] = __uint_as_float(w.y & 0xffff0000u); return r; }
;     __device__ __forceinline__ void fused(f32x4 (&acc)[2][2][4][2], const Unit& u, int wr, int wc, int fr, int fq, PG8_LAS unsigned char* lds, int wid, int lane) const {
;     ...
;             for (int m = 0; m < 4; ++m) { const int r = ai * HALF + wr * 64 + m * 16 + fr; const size_t off = (size_t)(u.pm * BM + r) * 2048 + col0; float s = 0.f;
;                 const float rr = __builtin_amdgcn_rcpf(r2[ai * 4 + m] * (1.0f / 2048.0f) + 1e-5f);
; #pragma unroll
;                 for (int bj = 0; bj < 2; ++bj)
; #pragma unroll
;                     for (int n = 0; n < 2; ++n) { const f32x4 bs = bf4_to_f32(*(const u32x2*)(base + off + bj * HALF + n * 16)); const f32x4 o = bs + acc[ai][bj][m][n] * rr; acc[ai][bj][m][n] = o;
.LBB0_1031:
	s_cmpk_eq_i32 s29, 118
	s_cbranch_scc0 .Lp5pf_skip
	s_lshl_b32 s46, s64, 8
	s_lshl_b32 s47, s18, 5
	s_lshl_b32 s48, s16, 8
	s_or_b32 s48, s48, s47
	v_add_u32_e32 v216, s46, v162
	v_ashrrev_i32_e32 v217, 31, v216
	v_lshlrev_b64 v[216:217], 12, v[216:217]
	v_lshl_add_u64 v[216:217], s[70:71], 0, v[216:217]
	v_and_or_b32 v192, v138, 12, s48
	v_lshlrev_b32_e32 v192, 1, v192
	v_mov_b32_e32 v193, 0
	v_lshl_add_u64 v[216:217], v[216:217], 0, v[192:193]
	s_mov_b64 s[46:47], 0x10000
	v_lshl_add_u64 v[192:193], v[216:217], 0, s[46:47]
	global_load_dwordx2 v[218:219], v[192:193], off
	global_load_dwordx2 v[220:221], v[192:193], off offset:32
	global_load_dwordx2 v[222:223], v[192:193], off offset:256
	global_load_dwordx2 v[224:225], v[192:193], off offset:288
	s_mov_b64 s[46:47], 0x20000
	v_lshl_add_u64 v[192:193], v[216:217], 0, s[46:47]
	global_load_dwordx2 v[226:227], v[192:193], off
	global_load_dwordx2 v[228:229], v[192:193], off offset:32
	global_load_dwordx2 v[230:231], v[192:193], off offset:256
	global_load_dwordx2 v[232:233], v[192:193], off offset:288
	s_mov_b64 s[46:47], 0x30000
	v_lshl_add_u64 v[192:193], v[216:217], 0, s[46:47]
	global_load_dwordx2 v[234:235], v[192:193], off
	global_load_dwordx2 v[236:237], v[192:193], off offset:32
	global_load_dwordx2 v[238:239], v[192:193], off offset:256
	global_load_dwordx2 v[240:241], v[192:193], off offset:288
	s_mov_b64 s[46:47], 0x80000
	v_lshl_add_u64 v[192:193], v[216:217], 0, s[46:47]
	global_load_dwordx2 v[244:245], v[192:193], off
	global_load_dwordx2 v[246:247], v[192:193], off offset:32
	global_load_dwordx2 v[248:249], v[192:193], off offset:256
	global_load_dwordx2 v[250:251], v[192:193], off offset:288

; __device__ __forceinline__ f32x4 bf4_to_f32(u32x2 w) { f32x4 r; r[0] = __uint_as_float(w.x << 16); r[1] = __uint_as_float(w.x & 0xffff0000u); r[2] = __uint_as_float(w.y << 16); r[3] = __uint_as_float(w.y & 0xffff0000u); return r; }
;     __device__ __forceinline__ void fused(f32x4 (&acc)[2][2][4][2], const Unit& u, int wr, int wc, int fr, int fq, PG8_LAS unsigned char* lds, int wid, int lane) const {
;     ...
;             for (int m = 0; m < 4; ++m) { const int r = ai * HALF + wr * 64 + m * 16 + fr; const size_t off = (size_t)(u.pm * BM + r) * 2048 + col0; float s = 0.f;
;                 const float rr = __builtin_amdgcn_rcpf(r2[ai * 4 + m] * (1.0f / 2048.0f) + 1e-5f);
; #pragma unroll
;                 for (int bj = 0; bj < 2; ++bj)
; #pragma unroll
;                     for (int n = 0; n < 2; ++n) { const f32x4 bs = bf4_to_f32(*(const u32x2*)(base + off + bj * HALF + n * 16)); const f32x4 o = bs + acc[ai][bj][m][n] * rr; acc[ai][bj][m][n] = o;
;                         s += (o[0] * o[0] + o[1] * o[1]) + (o[2] * o[2] + o[3] * o[3]); }
;                 s += __shfl_xor(s, 16); s += __shfl_xor(s, 32);
;                 if (fq == 0) P[r * 4 + wc] = s; }
.LBB0_1036:
	s_or_b64 exec, exec, s[2:3]
	v_or_b32_e32 v137, 16, v162
	v_add_u32_e32 v132, s0, v137
	s_waitcnt lgkmcnt(0)
	v_ashrrev_i32_e32 v133, 31, v132
	v_lshlrev_b64 v[148:149], 12, v[132:133]
	v_lshl_add_u64 v[148:149], s[70:71], 0, v[148:149]
	v_lshl_add_u64 v[148:149], v[148:149], 0, v[140:141]
	v_mov_b64_e32 v[150:151], v[218:219]
	v_mov_b64_e32 v[152:153], v[220:221]
	v_mov_b64_e32 v[154:155], v[222:223]
	v_mov_b64_e32 v[148:149], v[224:225]
	s_nop 0
	v_fmac_f32_e32 v135, 0x3a000000, v134
	v_rcp_f32_e32 v134, v135
	s_waitcnt vmcnt(3)
	v_lshlrev_b32_e32 v156, 16, v150
	v_and_b32_e32 v157, 0xffff0000, v150
	v_lshlrev_b32_e32 v150, 16, v151
	v_and_b32_e32 v151, 0xffff0000, v151
	s_waitcnt vmcnt(2)
	v_lshlrev_b32_e32 v158, 16, v152
	v_and_b32_e32 v159, 0xffff0000, v152
	v_lshlrev_b32_e32 v152, 16, v153
	v_and_b32_e32 v153, 0xffff0000, v153
	s_waitcnt vmcnt(1)
	v_lshlrev_b32_e32 v164, 16, v154
	v_and_b32_e32 v165, 0xffff0000, v154
	v_lshlrev_b32_e32 v154, 16, v155
	v_and_b32_e32 v155, 0xffff0000, v155
	s_waitcnt vmcnt(0)
	v_lshlrev_b32_e32 v166, 16, v148
	v_and_b32_e32 v167, 0xffff0000, v148
	v_lshlrev_b32_e32 v148, 16, v149
	v_and_b32_e32 v149, 0xffff0000, v149
	v_pk_fma_f32 v[112:113], v[112:113], v[134:135], v[150:151] op_sel_hi:[1,0,1]
	v_pk_fma_f32 v[110:111], v[110:111], v[134:135], v[156:157] op_sel_hi:[1,0,1]
	v_pk_fma_f32 v[108:109], v[108:109], v[134:135], v[152:153] op_sel_hi:[1,0,1]
	v_pk_fma_f32 v[106:107], v[106:107], v[134:135], v[158:159] op_sel_hi:[1,0,1]
	v_pk_fma_f32 v[104:105], v[104:105], v[134:135], v[154:155] op_sel_hi:[1,0,1]
	v_pk_fma_f32 v[102:103], v[102:103], v[134:135], v[164:165] op_sel_hi:[1,0,1]
	v_pk_fma_f32 v[100:101], v[100:101], v[134:135], v[148:149] op_sel_hi:[1,0,1]
	v_pk_fma_f32 v[98:99], v[98:99], v[134:135], v[166:167] op_sel_hi:[1,0,1]
	v_mul_f32_e32 v134, v111, v111
	v_mul_f32_e32 v135, v113, v113
	v_mul_f32_e32 v138, v107, v107
	v_mul_f32_e32 v141, v109, v109
	v_mul_f32_e32 v143, v103, v103
	v_mul_f32_e32 v145, v105, v105
	v_fmac_f32_e32 v134, v110, v110
	v_fmac_f32_e32 v135, v112, v112
	v_fmac_f32_e32 v138, v106, v106
	v_fmac_f32_e32 v141, v108, v108
	v_mul_f32_e32 v147, v99, v99
	v_mul_f32_e32 v148, v101, v101
	v_fmac_f32_e32 v143, v102, v102
	v_fmac_f32_e32 v145, v104, v104
	v_add_f32_e32 v134, v134, v135
	v_add_f32_e32 v135, v138, v141
	v_fmac_f32_e32 v147, v98, v98
	v_fmac_f32_e32 v148, v100, v100
	v_add_f32_e32 v138, v143, v145
	v_add_f32_e32 v134, v134, v135
	v_add_f32_e32 v134, v134, v138
	v_add_f32_e32 v135, v147, v148
	v_add_f32_e32 v134, v134, v135
	ds_bpermute_b32 v135, v161, v134
	s_waitcnt lgkmcnt(0)
	v_add_f32_e32 v134, v134, v135
	ds_bpermute_b32 v135, v163, v134
	s_and_saveexec_b64 s[2:3], vcc
	s_cbranch_execz .LBB0_1038
	v_lshl_add_u32 v137, v137, 4, s1
	s_waitcnt lgkmcnt(0)
	v_add_f32_e32 v134, v134, v135
	ds_write_b32 v137, v134
.LBB0_1038:
	s_or_b64 exec, exec, s[2:3]
	v_or_b32_e32 v143, 32, v162
	v_add_u32_e32 v134, s0, v143
	s_waitcnt lgkmcnt(0)
	v_ashrrev_i32_e32 v135, 31, v134
	v_lshlrev_b64 v[148:149], 12, v[134:135]
	v_lshl_add_u64 v[148:149], s[70:71], 0, v[148:149]
	v_mov_b32_e32 v141, 0
	v_lshl_add_u64 v[148:149], v[148:149], 0, v[140:141]
	v_mov_b64_e32 v[150:151], v[226:227]
	v_mov_b64_e32 v[152:153], v[228:229]
	v_mov_b64_e32 v[154:155], v[230:231]
	v_mov_b64_e32 v[148:149], v[232:233]
	s_nop 0
	v_mov_b32_e32 v138, 0x3727c5ac
	v_fmamk_f32 v136, v136, 0x3a000000, v138
	v_rcp_f32_e32 v156, v136
	s_waitcnt vmcnt(3)
	v_lshlrev_b32_e32 v136, 16, v150
	v_and_b32_e32 v137, 0xffff0000, v150
	v_lshlrev_b32_e32 v150, 16, v151
	v_and_b32_e32 v151, 0xffff0000, v151
	s_waitcnt vmcnt(2)
	v_lshlrev_b32_e32 v158, 16, v152
	v_and_b32_e32 v159, 0xffff0000, v152
	v_lshlrev_b32_e32 v152, 16, v153
	v_and_b32_e32 v153, 0xffff0000, v153
	s_waitcnt vmcnt(1)
	v_lshlrev_b32_e32 v164, 16, v154
	v_and_b32_e32 v165, 0xffff0000, v154
	v_lshlrev_b32_e32 v154, 16, v155
	v_and_b32_e32 v155, 0xffff0000, v155
	s_waitcnt vmcnt(0)
	v_lshlrev_b32_e32 v166, 16, v148
	v_and_b32_e32 v167, 0xffff0000, v148
	v_pk_fma_f32 v[96:97], v[96:97], v[156:157], v[150:151] op_sel_hi:[1,0,1]
	v_pk_fma_f32 v[136:137], v[94:95], v[156:157], v[136:137] op_sel_hi:[1,0,1]
	v_pk_fma_f32 v[92:93], v[92:93], v[156:157], v[152:153] op_sel_hi:[1,0,1]
	v_pk_fma_f32 v[94:95], v[90:91], v[156:157], v[158:159] op_sel_hi:[1,0,1]
	v_lshlrev_b32_e32 v148, 16, v149
	v_and_b32_e32 v149, 0xffff0000, v149
	v_pk_fma_f32 v[88:89], v[88:89], v[156:157], v[154:155] op_sel_hi:[1,0,1]
	v_pk_fma_f32 v[90:91], v[86:87], v[156:157], v[164:165] op_sel_hi:[1,0,1]
	v_pk_fma_f32 v[86:87], v[82:83], v[156:157], v[166:167] op_sel_hi:[1,0,1]
	v_mul_f32_e32 v82, v137, v137
	v_mul_f32_e32 v83, v97, v97
	v_mul_f32_e32 v145, v95, v95
	v_mul_f32_e32 v147, v93, v93
	v_pk_fma_f32 v[84:85], v[84:85], v[156:157], v[148:149] op_sel_hi:[1,0,1]
	v_mul_f32_e32 v148, v91, v91
	v_mul_f32_e32 v149, v89, v89
	v_fmac_f32_e32 v82, v136, v136
	v_fmac_f32_e32 v83, v96, v96
	v_fmac_f32_e32 v145, v94, v94
	v_fmac_f32_e32 v147, v92, v92
	v_mul_f32_e32 v150, v87, v87
	v_mul_f32_e32 v151, v85, v85
	v_fmac_f32_e32 v148, v90, v90
	v_fmac_f32_e32 v149, v88, v88
	v_add_f32_e32 v82, v82, v83
	v_add_f32_e32 v83, v145, v147
	v_fmac_f32_e32 v150, v86, v86
	v_fmac_f32_e32 v151, v84, v84
	v_add_f32_e32 v145, v148, v149
	v_add_f32_e32 v82, v82, v83
	v_add_f32_e32 v82, v82, v145
	v_add_f32_e32 v83, v150, v151
	v_add_f32_e32 v82, v82, v83
	ds_bpermute_b32 v83, v161, v82
	s_waitcnt lgkmcnt(0)
	v_add_f32_e32 v82, v82, v83
	ds_bpermute_b32 v83, v163, v82
	s_and_saveexec_b64 s[2:3], vcc
	s_cbranch_execz .LBB0_1040
	v_lshl_add_u32 v143, v143, 4, s1
	s_waitcnt lgkmcnt(0)
	v_add_f32_e32 v82, v82, v83
	ds_write_b32 v143, v82
; __device__ __forceinline__ f32x4 bf4_to_f32(u32x2 w) { f32x4 r; r[0] = __uint_as_float(w.x << 16); r[1] = __uint_as_float(w.x & 0xffff0000u); r[2] = __uint_as_float(w.y << 16); r[3] = __uint_as_float(w.y & 0xffff0000u); return r; }
;     __device__ __forceinline__ void fused(f32x4 (&acc)[2][2][4][2], const Unit& u, int wr, int wc, int fr, int fq, PG8_LAS unsigned char* lds, int wid, int lane) const {
;     ...
;             for (int m = 0; m < 4; ++m) { const int r = ai * HALF + wr * 64 + m * 16 + fr; const size_t off = (size_t)(u.pm * BM + r) * 2048 + col0; float s = 0.f;
;                 const float rr = __builtin_amdgcn_rcpf(r2[ai * 4 + m] * (1.0f / 2048.0f) + 1e-5f);
; #pragma unroll
;                 for (int bj = 0; bj < 2; ++bj)
; #pragma unroll
;                     for (int n = 0; n < 2; ++n) { const f32x4 bs = bf4_to_f32(*(const u32x2*)(base + off + bj * HALF + n * 16)); const f32x4 o = bs + acc[ai][bj][m][n] * rr; acc[ai][bj][m][n] = o;
;                         s += (o[0] * o[0] + o[1] * o[1]) + (o[2] * o[2] + o[3] * o[3]); }
;                 s += __shfl_xor(s, 16); s += __shfl_xor(s, 32);
;                 if (fq == 0) P[r * 4 + wc] = s; }
.LBB0_1040:
	s_or_b64 exec, exec, s[2:3]
	v_or_b32_e32 v143, 48, v162
	v_add_u32_e32 v82, s0, v143
	s_waitcnt lgkmcnt(0)
	v_ashrrev_i32_e32 v83, 31, v82
	v_lshlrev_b64 v[148:149], 12, v[82:83]
	v_lshl_add_u64 v[148:149], s[70:71], 0, v[148:149]
	v_lshl_add_u64 v[148:149], v[148:149], 0, v[140:141]
	v_mov_b64_e32 v[150:151], v[234:235]
	v_mov_b64_e32 v[152:153], v[236:237]
	v_mov_b64_e32 v[154:155], v[238:239]
	v_mov_b64_e32 v[148:149], v[240:241]
	s_nop 0
	v_fmac_f32_e32 v138, 0x3a000000, v139
	v_rcp_f32_e32 v138, v138
	s_waitcnt vmcnt(3)
	v_lshlrev_b32_e32 v156, 16, v150
	v_and_b32_e32 v157, 0xffff0000, v150
	v_lshlrev_b32_e32 v150, 16, v151
	v_and_b32_e32 v151, 0xffff0000, v151
	s_waitcnt vmcnt(2)
	v_lshlrev_b32_e32 v158, 16, v152
	v_and_b32_e32 v159, 0xffff0000, v152
	v_lshlrev_b32_e32 v152, 16, v153
	v_and_b32_e32 v153, 0xffff0000, v153
	s_waitcnt vmcnt(1)
	v_lshlrev_b32_e32 v164, 16, v154
	v_and_b32_e32 v165, 0xffff0000, v154
	v_lshlrev_b32_e32 v154, 16, v155
	v_and_b32_e32 v155, 0xffff0000, v155
	s_waitcnt vmcnt(0)
	v_lshlrev_b32_e32 v166, 16, v148
	v_and_b32_e32 v167, 0xffff0000, v148
	v_lshlrev_b32_e32 v148, 16, v149
	v_and_b32_e32 v149, 0xffff0000, v149
	v_pk_fma_f32 v[80:81], v[80:81], v[138:139], v[150:151] op_sel_hi:[1,0,1]
	v_pk_fma_f32 v[78:79], v[78:79], v[138:139], v[156:157] op_sel_hi:[1,0,1]
	v_pk_fma_f32 v[76:77], v[76:77], v[138:139], v[152:153] op_sel_hi:[1,0,1]
	v_pk_fma_f32 v[74:75], v[74:75], v[138:139], v[158:159] op_sel_hi:[1,0,1]
	v_pk_fma_f32 v[72:73], v[72:73], v[138:139], v[154:155] op_sel_hi:[1,0,1]
	v_pk_fma_f32 v[70:71], v[70:71], v[138:139], v[164:165] op_sel_hi:[1,0,1]
	v_pk_fma_f32 v[68:69], v[68:69], v[138:139], v[148:149] op_sel_hi:[1,0,1]
	v_pk_fma_f32 v[66:67], v[66:67], v[138:139], v[166:167] op_sel_hi:[1,0,1]
	v_mul_f32_e32 v138, v79, v79
	v_mul_f32_e32 v139, v81, v81
	v_mul_f32_e32 v141, v75, v75
	v_mul_f32_e32 v145, v77, v77
	v_mul_f32_e32 v147, v71, v71
	v_mul_f32_e32 v148, v73, v73
	v_fmac_f32_e32 v138, v78, v78
	v_fmac_f32_e32 v139, v80, v80
	v_fmac_f32_e32 v141, v74, v74
	v_fmac_f32_e32 v145, v76, v76
	v_mul_f32_e32 v149, v67, v67
	v_mul_f32_e32 v150, v69, v69
	v_fmac_f32_e32 v147, v70, v70
	v_fmac_f32_e32 v148, v72, v72
	v_add_f32_e32 v138, v138, v139
	v_add_f32_e32 v139, v141, v145
	v_fmac_f32_e32 v149, v66, v66
	v_fmac_f32_e32 v150, v68, v68
	v_add_f32_e32 v141, v147, v148
	v_add_f32_e32 v138, v138, v139
	v_add_f32_e32 v138, v138, v141
	v_add_f32_e32 v139, v149, v150
	v_add_f32_e32 v138, v138, v139
	ds_bpermute_b32 v139, v161, v138
	s_waitcnt lgkmcnt(0)
	v_add_f32_e32 v138, v138, v139
	ds_bpermute_b32 v139, v163, v138
	s_and_saveexec_b64 s[2:3], vcc
	s_cbranch_execz .LBB0_1042
	v_lshl_add_u32 v141, v143, 4, s1
	s_waitcnt lgkmcnt(0)
	v_add_f32_e32 v138, v138, v139
	ds_write_b32 v141, v138
.LBB0_1042:
	s_or_b64 exec, exec, s[2:3]
	v_add_u32_e32 v143, 0x80, v162
	v_add_u32_e32 v138, s0, v143
	s_waitcnt lgkmcnt(0)
	v_ashrrev_i32_e32 v139, 31, v138
	v_lshlrev_b64 v[148:149], 12, v[138:139]
	v_lshl_add_u64 v[148:149], s[70:71], 0, v[148:149]
	v_mov_b32_e32 v141, 0
	v_lshl_add_u64 v[148:149], v[148:149], 0, v[140:141]
	v_mov_b64_e32 v[150:151], v[244:245]
	v_mov_b64_e32 v[152:153], v[246:247]
	v_mov_b64_e32 v[154:155], v[248:249]
	v_mov_b64_e32 v[148:149], v[250:251]
	s_nop 0
	v_mov_b32_e32 v145, 0x3727c5ac
	v_fmamk_f32 v142, v142, 0x3a000000, v145
	v_rcp_f32_e32 v142, v142
	s_waitcnt vmcnt(3)
	v_lshlrev_b32_e32 v156, 16, v150
	v_and_b32_e32 v157, 0xffff0000, v150
	v_lshlrev_b32_e32 v150, 16, v151
	v_and_b32_e32 v151, 0xffff0000, v151
	s_waitcnt vmcnt(2)
	v_lshlrev_b32_e32 v158, 16, v152
	v_and_b32_e32 v159, 0xffff0000, v152
	v_lshlrev_b32_e32 v152, 16, v153
	v_and_b32_e32 v153, 0xffff0000, v153
	s_waitcnt vmcnt(1)
	v_lshlrev_b32_e32 v164, 16, v154
	v_and_b32_e32 v165, 0xffff0000, v154
	v_lshlrev_b32_e32 v154, 16, v155
	v_and_b32_e32 v155, 0xffff0000, v155
	s_waitcnt vmcnt(0)
	v_lshlrev_b32_e32 v166, 16, v148
	v_and_b32_e32 v167, 0xffff0000, v148
	v_lshlrev_b32_e32 v148, 16, v149
	v_and_b32_e32 v149, 0xffff0000, v149
	v_pk_fma_f32 v[64:65], v[64:65], v[142:143], v[150:151] op_sel_hi:[1,0,1]
	v_pk_fma_f32 v[62:63], v[62:63], v[142:143], v[156:157] op_sel_hi:[1,0,1]
	v_pk_fma_f32 v[60:61], v[60:61], v[142:143], v[152:153] op_sel_hi:[1,0,1]
	v_pk_fma_f32 v[58:59], v[58:59], v[142:143], v[158:159] op_sel_hi:[1,0,1]
	v_pk_fma_f32 v[56:57], v[56:57], v[142:143], v[154:155] op_sel_hi:[1,0,1]
	v_pk_fma_f32 v[54:55], v[54:55], v[142:143], v[164:165] op_sel_hi:[1,0,1]
	v_pk_fma_f32 v[52:53], v[52:53], v[142:143], v[148:149] op_sel_hi:[1,0,1]
	v_pk_fma_f32 v[50:51], v[50:51], v[142:143], v[166:167] op_sel_hi:[1,0,1]
	v_mul_f32_e32 v142, v63, v63
	v_mul_f32_e32 v147, v65, v65
	v_mul_f32_e32 v148, v59, v59
	v_mul_f32_e32 v149, v61, v61
	v_mul_f32_e32 v150, v55, v55
	v_mul_f32_e32 v151, v57, v57
	v_fmac_f32_e32 v142, v62, v62
	v_fmac_f32_e32 v147, v64, v64
	v_fmac_f32_e32 v148, v58, v58
	v_fmac_f32_e32 v149, v60, v60
	v_mul_f32_e32 v152, v51, v51
	v_mul_f32_e32 v153, v53, v53
	v_fmac_f32_e32 v150, v54, v54
	v_fmac_f32_e32 v151, v56, v56
	v_add_f32_e32 v142, v142, v147
	v_add_f32_e32 v147, v148, v149
	v_fmac_f32_e32 v152, v50, v50
	v_fmac_f32_e32 v153, v52, v52
	v_add_f32_e32 v148, v150, v151
	v_add_f32_e32 v142, v142, v147
	v_add_f32_e32 v142, v142, v148
	v_add_f32_e32 v147, v152, v153
	v_add_f32_e32 v142, v142, v147
	ds_bpermute_b32 v147, v161, v142
	s_waitcnt lgkmcnt(0)
	v_add_f32_e32 v142, v142, v147
	ds_bpermute_b32 v147, v163, v142
	s_and_saveexec_b64 s[2:3], vcc
	s_cbranch_execz .LBB0_1044
	v_lshl_add_u32 v143, v143, 4, s1
	s_waitcnt lgkmcnt(0)
	v_add_f32_e32 v142, v142, v147
	ds_write_b32 v143, v142
